# e24: e18 + Y-unit GELU exponent argument formed with 3 dependent f32 ops instead of 6 (constants folded: q=y*y, p=q*C1+C0, z=y*p); same formula, f32
# speedup vs baseline: 1.0038x; 1.0038x over previous
; __device__ __forceinline__ float gelu_tanh_f(float y) { const float t = 0.7978845608028654f * (y + 0.044715f * y * y * y); return y * fast_sigmoid(2.f * t); }
; __device__ __forceinline__ u32x4 pack8(const f32x4 v0, const f32x4 v1) { u32x4 w; w.x = pk_f16(v0[0], v0[1]); w.y = pk_f16(v0[2], v0[3]); w.z = pk_f16(v1[0], v1[1]); w.w = pk_f16(v1[2], v1[3]); return w; }
; __device__ __forceinline__ void unpack8(const u32x4 w, f32x4& v0, f32x4& v1) { v0 = (f32x4){f16lo(w.x), f16hi(w.x), f16lo(w.y), f16hi(w.y)}; v1 = (f32x4){f16lo(w.z), f16hi(w.z), f16lo(w.w), f16hi(w.w)}; }
;     __device__ __forceinline__ void operator()(AccRef acc, const Unit& u, int wr, int wc, int fr, int fq) const {
;         int row0 = u.pm * 256 + wr * 64 + fr; asm volatile("" : "+v"(row0)); int col0 = u.pn * 256 + wc * 32 + 8 * fq; asm volatile("" : "+v"(col0));
;         const float* dp = dskip + u.g * GH + (col0 & 15);
;         const f32x4 d0 = *(const f32x4*)dp, d1 = *(const f32x4*)(dp + 4);
;         const f16* Xg = X + (size_t)u.g * XGS + 256 + col0; f16* Yg = YG + (size_t)u.g * YGS + col0;
; #pragma unroll
;         for (int ai = 0; ai < 2; ++ai) { u32x4 uv[4][2];
; #pragma unroll
;             for (int m = 0; m < 4; ++m)
; #pragma unroll
;                 for (int bj = 0; bj < 2; ++bj) uv[m][bj] = *(const u32x4*)(Xg + (size_t)(row0 + ai * HALF + m * 16) * XK + bj * HALF);
;             __builtin_amdgcn_sched_barrier(0);
; #pragma unroll
;             for (int m = 0; m < 4; ++m)
; #pragma unroll
;                 for (int bj = 0; bj < 2; ++bj) { f32x4 u0, u1; unpack8(uv[m][bj], u0, u1);
;                     f32x4 v0 = acc[ai][bj][m][0] + d0 * u0, v1 = acc[ai][bj][m][1] + d1 * u1;
; #pragma unroll
;                     for (int j = 0; j < 4; ++j) { v0[j] = gelu_tanh_f(v0[j]); v1[j] = gelu_tanh_f(v1[j]); }
;                     *(u32x4*)(Yg + (size_t)(row0 + ai * HALF + m * 16) * 512 + bj * HALF) = pack8(v0, v1); } }
.LBB0_996:
	s_mov_b32 s99, 0xbdd2d3e7
	v_mov_b32_e32 v255, 0xc0135761
	v_lshl_or_b32 v1, s0, 8, v215
	s_lshl_b32 s0, s24, 4
	s_ashr_i32 s1, s0, 31
	v_lshl_add_u32 v164, s84, 8, v27
	v_or_b32_e32 v106, s54, v1
	s_lshl_b64 s[0:1], s[0:1], 2
	s_add_u32 s0, s38, s0
	v_and_b32_e32 v1, 15, v106
	v_ashrrev_i32_e32 v107, 31, v106
	s_addc_u32 s1, s39, s1
	v_lshlrev_b32_e32 v1, 2, v1
	v_lshlrev_b64 v[162:163], 1, v[106:107]
	global_load_dwordx4 v[26:29], v1, s[0:1] offset:16
	global_load_dwordx4 v[30:33], v1, s[0:1]
	v_lshl_add_u64 v[166:167], s[2:3], 0, v[162:163]
	s_movk_i32 s0, 0x600
	v_mad_i64_i32 v[106:107], s[2:3], v164, s0, v[166:167]
	v_add_u32_e32 v172, 16, v164
	global_load_dwordx4 v[176:179], v[106:107], off offset:512
	global_load_dwordx4 v[180:183], v[106:107], off offset:768
	v_mad_i64_i32 v[106:107], s[2:3], v172, s0, v[166:167]
	v_add_u32_e32 v170, 32, v164
	global_load_dwordx4 v[158:161], v[106:107], off offset:512
	global_load_dwordx4 v[154:157], v[106:107], off offset:768
	v_mad_i64_i32 v[106:107], s[2:3], v170, s0, v[166:167]
	v_add_u32_e32 v168, 48, v164
	global_load_dwordx4 v[142:145], v[106:107], off offset:512
	global_load_dwordx4 v[130:133], v[106:107], off offset:768
	v_mad_i64_i32 v[106:107], s[2:3], v168, s0, v[166:167]
	global_load_dwordx4 v[118:121], v[106:107], off offset:512
	s_nop 0
	global_load_dwordx4 v[106:109], v[106:107], off offset:768
	s_lshl_b64 s[2:3], s[24:25], 19
	s_add_u32 s2, s50, s2
	s_addc_u32 s3, s51, s3
	v_lshl_add_u64 v[162:163], s[2:3], 0, v[162:163]
	s_mov_b64 s[2:3], 0x17800000
	v_lshl_add_u64 v[162:163], v[162:163], 0, s[2:3]
	v_ashrrev_i32_e32 v165, 31, v164
	v_ashrrev_i32_e32 v173, 31, v172
	v_ashrrev_i32_e32 v171, 31, v170
	v_ashrrev_i32_e32 v169, 31, v168
	s_waitcnt vmcnt(0)
	v_and_b32_e32 v185, 0xffff0000, v176
	v_lshlrev_b32_e32 v184, 16, v176
	v_and_b32_e32 v187, 0xffff0000, v177
	v_lshlrev_b32_e32 v186, 16, v177
	v_and_b32_e32 v177, 0xffff0000, v178
	v_lshlrev_b32_e32 v176, 16, v178
	v_pk_fma_f32 v[150:151], v[30:31], v[184:185], v[150:151]
	v_pk_fma_f32 v[146:147], v[26:27], v[176:177], v[146:147]
	v_lshlrev_b64 v[174:175], 10, v[164:165]
	v_mul_f32_e32 v1, v150, v150
	v_mul_f32_e32 v165, v146, v146
	v_mul_f32_e32 v176, v151, v151
	v_fma_f32 v1, v1, s99, v255
	v_fma_f32 v165, v165, s99, v255
	v_fma_f32 v176, v176, s99, v255
	v_mul_f32_e32 v1, v150, v1
	v_mul_f32_e32 v165, v146, v165
	v_mul_f32_e32 v176, v151, v176
	v_exp_f32_e32 v1, v1
	v_exp_f32_e32 v165, v165
	v_exp_f32_e32 v176, v176
	v_mul_f32_e32 v177, v147, v147
	v_add_f32_e32 v1, 1.0, v1
	v_add_f32_e32 v165, 1.0, v165
	v_add_f32_e32 v176, 1.0, v176
	v_rcp_f32_e32 v1, v1
	v_rcp_f32_e32 v165, v165
	v_rcp_f32_e32 v176, v176
	v_fma_f32 v177, v177, s99, v255
	v_mul_f32_e32 v177, v147, v177
	v_and_b32_e32 v189, 0xffff0000, v179
	v_lshlrev_b32_e32 v188, 16, v179
	v_pk_fma_f32 v[152:153], v[32:33], v[186:187], v[152:153]
	v_pk_fma_f32 v[148:149], v[28:29], v[188:189], v[148:149]
	v_mul_f32_e32 v1, v150, v1
	v_mul_f32_e32 v150, v146, v165
	v_mul_f32_e32 v146, v151, v176
	v_mul_f32_e32 v165, v152, v152
	v_mul_f32_e32 v176, v148, v148
	v_exp_f32_e32 v177, v177
	v_fma_f32 v165, v165, s99, v255
	v_fma_f32 v176, v176, s99, v255
	v_mul_f32_e32 v165, v152, v165
	v_mul_f32_e32 v176, v148, v176
	v_add_f32_e32 v151, 1.0, v177
	v_rcp_f32_e32 v151, v151
	v_exp_f32_e32 v165, v165
	v_exp_f32_e32 v176, v176
	v_mul_f32_e32 v177, v149, v149
	v_mul_f32_e32 v151, v147, v151
	v_add_f32_e32 v147, 1.0, v165
	v_add_f32_e32 v165, 1.0, v176
	v_mul_f32_e32 v176, v153, v153
	v_fma_f32 v176, v176, s99, v255
	v_fma_f32 v177, v177, s99, v255
	v_mul_f32_e32 v176, v153, v176
	v_mul_f32_e32 v177, v149, v177
	v_exp_f32_e32 v176, v176
	v_exp_f32_e32 v177, v177
	v_rcp_f32_e32 v147, v147
	v_rcp_f32_e32 v165, v165
	v_add_f32_e32 v176, 1.0, v176
	v_add_f32_e32 v177, 1.0, v177
	v_rcp_f32_e32 v176, v176
	v_rcp_f32_e32 v177, v177
	v_mul_f32_e32 v147, v152, v147
	v_mul_f32_e32 v152, v148, v165
	v_mul_f32_e32 v148, v153, v176
	v_mul_f32_e32 v149, v149, v177
	v_lshl_add_u64 v[174:175], v[162:163], 0, v[174:175]
	v_cvt_pk_bf16_f32 v146, v1, v146
	v_cvt_pk_bf16_f32 v147, v147, v148
	v_cvt_pk_bf16_f32 v148, v150, v151
	v_cvt_pk_bf16_f32 v149, v152, v149
	global_store_dwordx4 v[174:175], v[146:149], off
	v_and_b32_e32 v151, 0xffff0000, v182
	v_lshlrev_b32_e32 v150, 16, v182
	v_and_b32_e32 v147, 0xffff0000, v180
	v_lshlrev_b32_e32 v146, 16, v180
	v_pk_fma_f32 v[138:139], v[30:31], v[146:147], v[138:139]
	v_pk_fma_f32 v[134:135], v[26:27], v[150:151], v[134:135]
	v_mul_f32_e32 v1, v138, v138
	v_mul_f32_e32 v146, v134, v134
	v_mul_f32_e32 v147, v139, v139
	v_fma_f32 v1, v1, s99, v255
	v_fma_f32 v146, v146, s99, v255
	v_fma_f32 v147, v147, s99, v255
	v_mul_f32_e32 v1, v138, v1
	v_mul_f32_e32 v146, v134, v146
	v_mul_f32_e32 v147, v139, v147
	v_exp_f32_e32 v1, v1
	v_exp_f32_e32 v146, v146
	v_exp_f32_e32 v147, v147
	v_and_b32_e32 v149, 0xffff0000, v181
	v_lshlrev_b32_e32 v148, 16, v181
	v_pk_fma_f32 v[140:141], v[32:33], v[148:149], v[140:141]
	v_add_f32_e32 v1, 1.0, v1
	v_add_f32_e32 v146, 1.0, v146
	v_add_f32_e32 v147, 1.0, v147
	v_mul_f32_e32 v148, v135, v135
	v_rcp_f32_e32 v1, v1
	v_rcp_f32_e32 v146, v146
	v_rcp_f32_e32 v147, v147
	v_fma_f32 v148, v148, s99, v255
	v_mul_f32_e32 v148, v135, v148
	v_and_b32_e32 v153, 0xffff0000, v183
	v_lshlrev_b32_e32 v152, 16, v183
	v_pk_fma_f32 v[136:137], v[28:29], v[152:153], v[136:137]
	v_mul_f32_e32 v1, v138, v1
	v_mul_f32_e32 v138, v134, v146
	v_mul_f32_e32 v134, v139, v147
	v_mul_f32_e32 v146, v140, v140
	v_mul_f32_e32 v147, v136, v136
	v_exp_f32_e32 v148, v148
	v_fma_f32 v146, v146, s99, v255
	v_fma_f32 v147, v147, s99, v255
	v_mul_f32_e32 v146, v140, v146
; __device__ __forceinline__ float gelu_tanh_f(float y) { const float t = 0.7978845608028654f * (y + 0.044715f * y * y * y); return y * fast_sigmoid(2.f * t); }
; __device__ __forceinline__ u32x4 pack8(const f32x4 v0, const f32x4 v1) { u32x4 w; w.x = pk_f16(v0[0], v0[1]); w.y = pk_f16(v0[2], v0[3]); w.z = pk_f16(v1[0], v1[1]); w.w = pk_f16(v1[2], v1[3]); return w; }
; __device__ __forceinline__ void unpack8(const u32x4 w, f32x4& v0, f32x4& v1) { v0 = (f32x4){f16lo(w.x), f16hi(w.x), f16lo(w.y), f16hi(w.y)}; v1 = (f32x4){f16lo(w.z), f16hi(w.z), f16lo(w.w), f16hi(w.w)}; }
;     __device__ __forceinline__ void operator()(AccRef acc, const Unit& u, int wr, int wc, int fr, int fq) const {
;     ...
;             for (int m = 0; m < 4; ++m)
; #pragma unroll
;                 for (int bj = 0; bj < 2; ++bj) { f32x4 u0, u1; unpack8(uv[m][bj], u0, u1);
;                     f32x4 v0 = acc[ai][bj][m][0] + d0 * u0, v1 = acc[ai][bj][m][1] + d1 * u1;
; #pragma unroll
;                     for (int j = 0; j < 4; ++j) { v0[j] = gelu_tanh_f(v0[j]); v1[j] = gelu_tanh_f(v1[j]); }
;                     *(u32x4*)(Yg + (size_t)(row0 + ai * HALF + m * 16) * 512 + bj * HALF) = pack8(v0, v1); } }
	v_mul_f32_e32 v147, v136, v147
	v_add_f32_e32 v139, 1.0, v148
	v_rcp_f32_e32 v139, v139
	v_exp_f32_e32 v146, v146
	v_exp_f32_e32 v147, v147
	v_mul_f32_e32 v148, v137, v137
	v_mul_f32_e32 v139, v135, v139
	v_add_f32_e32 v135, 1.0, v146
	v_add_f32_e32 v146, 1.0, v147
	v_mul_f32_e32 v147, v141, v141
	v_fma_f32 v147, v147, s99, v255
	v_fma_f32 v148, v148, s99, v255
	v_mul_f32_e32 v147, v141, v147
	v_mul_f32_e32 v148, v137, v148
	v_exp_f32_e32 v147, v147
	v_exp_f32_e32 v148, v148
	v_rcp_f32_e32 v135, v135
	v_rcp_f32_e32 v146, v146
	v_add_f32_e32 v147, 1.0, v147
	v_add_f32_e32 v148, 1.0, v148
	v_rcp_f32_e32 v147, v147
	v_rcp_f32_e32 v148, v148
	v_mul_f32_e32 v135, v140, v135
	v_mul_f32_e32 v140, v136, v146
	v_mul_f32_e32 v136, v141, v147
	v_mul_f32_e32 v137, v137, v148
	v_cvt_pk_bf16_f32 v134, v1, v134
	v_cvt_pk_bf16_f32 v135, v135, v136
	v_cvt_pk_bf16_f32 v136, v138, v139
	v_cvt_pk_bf16_f32 v137, v140, v137
	global_store_dwordx4 v[174:175], v[134:137], off offset:256
	v_and_b32_e32 v141, 0xffff0000, v160
	v_lshlrev_b32_e32 v140, 16, v160
	v_and_b32_e32 v137, 0xffff0000, v158
	v_lshlrev_b32_e32 v136, 16, v158
	v_pk_fma_f32 v[126:127], v[30:31], v[136:137], v[126:127]
	v_pk_fma_f32 v[122:123], v[26:27], v[140:141], v[122:123]
	v_mul_f32_e32 v1, v126, v126
	v_mul_f32_e32 v136, v122, v122
	v_mul_f32_e32 v137, v127, v127
	v_fma_f32 v1, v1, s99, v255
	v_fma_f32 v136, v136, s99, v255
	v_fma_f32 v137, v137, s99, v255
	v_mul_f32_e32 v1, v126, v1
	v_mul_f32_e32 v136, v122, v136
	v_mul_f32_e32 v137, v127, v137
	v_exp_f32_e32 v1, v1
	v_exp_f32_e32 v136, v136
	v_exp_f32_e32 v137, v137
	v_and_b32_e32 v139, 0xffff0000, v159
	v_lshlrev_b32_e32 v138, 16, v159
	v_pk_fma_f32 v[128:129], v[32:33], v[138:139], v[128:129]
	v_add_f32_e32 v1, 1.0, v1
	v_add_f32_e32 v136, 1.0, v136
	v_add_f32_e32 v137, 1.0, v137
	v_mul_f32_e32 v138, v123, v123
	v_rcp_f32_e32 v1, v1
	v_rcp_f32_e32 v136, v136
	v_rcp_f32_e32 v137, v137
	v_fma_f32 v138, v138, s99, v255
	v_mul_f32_e32 v138, v123, v138
	v_and_b32_e32 v147, 0xffff0000, v161
	v_lshlrev_b32_e32 v146, 16, v161
	v_pk_fma_f32 v[124:125], v[28:29], v[146:147], v[124:125]
	v_mul_f32_e32 v1, v126, v1
	v_mul_f32_e32 v126, v122, v136
	v_mul_f32_e32 v122, v127, v137
	v_mul_f32_e32 v136, v128, v128
	v_mul_f32_e32 v137, v124, v124
	v_exp_f32_e32 v138, v138
	v_fma_f32 v136, v136, s99, v255
	v_fma_f32 v137, v137, s99, v255
	v_mul_f32_e32 v136, v128, v136
	v_mul_f32_e32 v137, v124, v137
	v_add_f32_e32 v127, 1.0, v138
	v_rcp_f32_e32 v127, v127
	v_exp_f32_e32 v136, v136
	v_exp_f32_e32 v137, v137
	v_mul_f32_e32 v138, v125, v125
	v_mul_f32_e32 v127, v123, v127
	v_add_f32_e32 v123, 1.0, v136
	v_add_f32_e32 v136, 1.0, v137
	v_mul_f32_e32 v137, v129, v129
	v_fma_f32 v137, v137, s99, v255
	v_fma_f32 v138, v138, s99, v255
	v_mul_f32_e32 v137, v129, v137
	v_mul_f32_e32 v138, v125, v138
	v_exp_f32_e32 v137, v137
	v_exp_f32_e32 v138, v138
	v_rcp_f32_e32 v123, v123
	v_rcp_f32_e32 v136, v136
	v_add_f32_e32 v137, 1.0, v137
	v_add_f32_e32 v138, 1.0, v138
	v_rcp_f32_e32 v137, v137
	v_rcp_f32_e32 v138, v138
	v_lshlrev_b64 v[134:135], 10, v[172:173]
	v_mul_f32_e32 v123, v128, v123
	v_mul_f32_e32 v128, v124, v136
	v_mul_f32_e32 v124, v129, v137
	v_mul_f32_e32 v125, v125, v138
	v_lshl_add_u64 v[134:135], v[162:163], 0, v[134:135]
	v_cvt_pk_bf16_f32 v122, v1, v122
	v_cvt_pk_bf16_f32 v123, v123, v124
	v_cvt_pk_bf16_f32 v124, v126, v127
	v_cvt_pk_bf16_f32 v125, v128, v125
	global_store_dwordx4 v[134:135], v[122:125], off
	v_and_b32_e32 v127, 0xffff0000, v156
	v_lshlrev_b32_e32 v126, 16, v156
	v_and_b32_e32 v123, 0xffff0000, v154
	v_lshlrev_b32_e32 v122, 16, v154
	v_pk_fma_f32 v[114:115], v[30:31], v[122:123], v[114:115]
	v_pk_fma_f32 v[110:111], v[26:27], v[126:127], v[110:111]
	v_mul_f32_e32 v1, v114, v114
	v_mul_f32_e32 v122, v110, v110
	v_mul_f32_e32 v123, v115, v115
	v_fma_f32 v1, v1, s99, v255
	v_fma_f32 v122, v122, s99, v255
	v_fma_f32 v123, v123, s99, v255
	v_mul_f32_e32 v1, v114, v1
	v_mul_f32_e32 v122, v110, v122
	v_mul_f32_e32 v123, v115, v123
	v_exp_f32_e32 v1, v1
	v_exp_f32_e32 v122, v122
	v_exp_f32_e32 v123, v123
	v_and_b32_e32 v125, 0xffff0000, v155
	v_lshlrev_b32_e32 v124, 16, v155
	v_pk_fma_f32 v[116:117], v[32:33], v[124:125], v[116:117]
	v_add_f32_e32 v1, 1.0, v1
	v_add_f32_e32 v122, 1.0, v122
	v_add_f32_e32 v123, 1.0, v123
	v_mul_f32_e32 v124, v111, v111
	v_rcp_f32_e32 v1, v1
	v_rcp_f32_e32 v122, v122
	v_rcp_f32_e32 v123, v123
	v_fma_f32 v124, v124, s99, v255
	v_mul_f32_e32 v124, v111, v124
	v_and_b32_e32 v129, 0xffff0000, v157
	v_lshlrev_b32_e32 v128, 16, v157
	v_pk_fma_f32 v[112:113], v[28:29], v[128:129], v[112:113]
	v_mul_f32_e32 v1, v114, v1
	v_mul_f32_e32 v114, v110, v122
	v_mul_f32_e32 v110, v115, v123
	v_mul_f32_e32 v122, v116, v116
	v_mul_f32_e32 v123, v112, v112
	v_exp_f32_e32 v124, v124
	v_fma_f32 v122, v122, s99, v255
	v_fma_f32 v123, v123, s99, v255
	v_mul_f32_e32 v122, v116, v122
	v_mul_f32_e32 v123, v112, v123
	v_add_f32_e32 v115, 1.0, v124
	v_rcp_f32_e32 v115, v115
	v_exp_f32_e32 v122, v122
	v_exp_f32_e32 v123, v123
	v_mul_f32_e32 v124, v113, v113
	v_mul_f32_e32 v115, v111, v115
	v_add_f32_e32 v111, 1.0, v122
	v_add_f32_e32 v122, 1.0, v123
	v_mul_f32_e32 v123, v117, v117
	v_fma_f32 v123, v123, s99, v255
	v_fma_f32 v124, v124, s99, v255
	v_mul_f32_e32 v123, v117, v123
	v_mul_f32_e32 v124, v113, v124
	v_exp_f32_e32 v123, v123
	v_exp_f32_e32 v124, v124
	v_rcp_f32_e32 v111, v111
	v_rcp_f32_e32 v122, v122
	v_add_f32_e32 v123, 1.0, v123
	v_add_f32_e32 v124, 1.0, v124
	v_rcp_f32_e32 v123, v123
	v_rcp_f32_e32 v124, v124
	v_mul_f32_e32 v111, v116, v111
	v_mul_f32_e32 v116, v112, v122
	v_mul_f32_e32 v112, v117, v123
	v_mul_f32_e32 v113, v113, v124
; __device__ __forceinline__ float gelu_tanh_f(float y) { const float t = 0.7978845608028654f * (y + 0.044715f * y * y * y); return y * fast_sigmoid(2.f * t); }
; __device__ __forceinline__ u32x4 pack8(const f32x4 v0, const f32x4 v1) { u32x4 w; w.x = pk_f16(v0[0], v0[1]); w.y = pk_f16(v0[2], v0[3]); w.z = pk_f16(v1[0], v1[1]); w.w = pk_f16(v1[2], v1[3]); return w; }
; __device__ __forceinline__ void unpack8(const u32x4 w, f32x4& v0, f32x4& v1) { v0 = (f32x4){f16lo(w.x), f16hi(w.x), f16lo(w.y), f16hi(w.y)}; v1 = (f32x4){f16lo(w.z), f16hi(w.z), f16lo(w.w), f16hi(w.w)}; }
;     __device__ __forceinline__ void operator()(AccRef acc, const Unit& u, int wr, int wc, int fr, int fq) const {
;     ...
;             for (int m = 0; m < 4; ++m)
; #pragma unroll
;                 for (int bj = 0; bj < 2; ++bj) { f32x4 u0, u1; unpack8(uv[m][bj], u0, u1);
;                     f32x4 v0 = acc[ai][bj][m][0] + d0 * u0, v1 = acc[ai][bj][m][1] + d1 * u1;
; #pragma unroll
;                     for (int j = 0; j < 4; ++j) { v0[j] = gelu_tanh_f(v0[j]); v1[j] = gelu_tanh_f(v1[j]); }
;                     *(u32x4*)(Yg + (size_t)(row0 + ai * HALF + m * 16) * 512 + bj * HALF) = pack8(v0, v1); } }
	v_cvt_pk_bf16_f32 v110, v1, v110
	v_cvt_pk_bf16_f32 v111, v111, v112
	v_cvt_pk_bf16_f32 v112, v114, v115
	v_cvt_pk_bf16_f32 v113, v116, v113
	global_store_dwordx4 v[134:135], v[110:113], off offset:256
	v_and_b32_e32 v117, 0xffff0000, v144
	v_lshlrev_b32_e32 v116, 16, v144
	v_and_b32_e32 v113, 0xffff0000, v142
	v_lshlrev_b32_e32 v112, 16, v142
	v_pk_fma_f32 v[102:103], v[30:31], v[112:113], v[102:103]
	v_pk_fma_f32 v[98:99], v[26:27], v[116:117], v[98:99]
	v_mul_f32_e32 v1, v102, v102
	v_mul_f32_e32 v112, v98, v98
	v_mul_f32_e32 v113, v103, v103
	v_fma_f32 v1, v1, s99, v255
	v_fma_f32 v112, v112, s99, v255
	v_fma_f32 v113, v113, s99, v255
	v_mul_f32_e32 v1, v102, v1
	v_mul_f32_e32 v112, v98, v112
	v_mul_f32_e32 v113, v103, v113
	v_exp_f32_e32 v1, v1
	v_exp_f32_e32 v112, v112
	v_exp_f32_e32 v113, v113
	v_and_b32_e32 v115, 0xffff0000, v143
	v_lshlrev_b32_e32 v114, 16, v143
	v_pk_fma_f32 v[104:105], v[32:33], v[114:115], v[104:105]
	v_add_f32_e32 v1, 1.0, v1
	v_add_f32_e32 v112, 1.0, v112
	v_add_f32_e32 v113, 1.0, v113
	v_mul_f32_e32 v114, v99, v99
	v_rcp_f32_e32 v1, v1
	v_rcp_f32_e32 v112, v112
	v_rcp_f32_e32 v113, v113
	v_fma_f32 v114, v114, s99, v255
	v_mul_f32_e32 v114, v99, v114
	v_and_b32_e32 v123, 0xffff0000, v145
	v_lshlrev_b32_e32 v122, 16, v145
	v_pk_fma_f32 v[100:101], v[28:29], v[122:123], v[100:101]
	v_mul_f32_e32 v1, v102, v1
	v_mul_f32_e32 v102, v98, v112
	v_mul_f32_e32 v98, v103, v113
	v_mul_f32_e32 v112, v104, v104
	v_mul_f32_e32 v113, v100, v100
	v_exp_f32_e32 v114, v114
	v_fma_f32 v112, v112, s99, v255
	v_fma_f32 v113, v113, s99, v255
	v_mul_f32_e32 v112, v104, v112
	v_mul_f32_e32 v113, v100, v113
	v_add_f32_e32 v103, 1.0, v114
	v_rcp_f32_e32 v103, v103
	v_exp_f32_e32 v112, v112
	v_exp_f32_e32 v113, v113
	v_mul_f32_e32 v114, v101, v101
	v_mul_f32_e32 v103, v99, v103
	v_add_f32_e32 v99, 1.0, v112
	v_add_f32_e32 v112, 1.0, v113
	v_mul_f32_e32 v113, v105, v105
	v_fma_f32 v113, v113, s99, v255
	v_fma_f32 v114, v114, s99, v255
	v_mul_f32_e32 v113, v105, v113
	v_mul_f32_e32 v114, v101, v114
	v_exp_f32_e32 v113, v113
	v_exp_f32_e32 v114, v114
	v_rcp_f32_e32 v99, v99
	v_rcp_f32_e32 v112, v112
	v_add_f32_e32 v113, 1.0, v113
	v_add_f32_e32 v114, 1.0, v114
	v_rcp_f32_e32 v113, v113
	v_rcp_f32_e32 v114, v114
	v_lshlrev_b64 v[110:111], 10, v[170:171]
	v_mul_f32_e32 v99, v104, v99
	v_mul_f32_e32 v104, v100, v112
	v_mul_f32_e32 v100, v105, v113
	v_mul_f32_e32 v101, v101, v114
	v_lshl_add_u64 v[110:111], v[162:163], 0, v[110:111]
	v_cvt_pk_bf16_f32 v98, v1, v98
	v_cvt_pk_bf16_f32 v99, v99, v100
	v_cvt_pk_bf16_f32 v100, v102, v103
	v_cvt_pk_bf16_f32 v101, v104, v101
	global_store_dwordx4 v[110:111], v[98:101], off
	v_and_b32_e32 v103, 0xffff0000, v132
	v_lshlrev_b32_e32 v102, 16, v132
	v_and_b32_e32 v99, 0xffff0000, v130
	v_lshlrev_b32_e32 v98, 16, v130
	v_pk_fma_f32 v[94:95], v[30:31], v[98:99], v[94:95]
	v_pk_fma_f32 v[90:91], v[26:27], v[102:103], v[90:91]
	v_mul_f32_e32 v1, v94, v94
	v_mul_f32_e32 v98, v90, v90
	v_mul_f32_e32 v99, v95, v95
	v_fma_f32 v1, v1, s99, v255
	v_fma_f32 v98, v98, s99, v255
	v_fma_f32 v99, v99, s99, v255
	v_mul_f32_e32 v1, v94, v1
	v_mul_f32_e32 v98, v90, v98
	v_mul_f32_e32 v99, v95, v99
	v_exp_f32_e32 v1, v1
	v_exp_f32_e32 v98, v98
	v_exp_f32_e32 v99, v99
	v_and_b32_e32 v101, 0xffff0000, v131
	v_lshlrev_b32_e32 v100, 16, v131
	v_pk_fma_f32 v[96:97], v[32:33], v[100:101], v[96:97]
	v_add_f32_e32 v1, 1.0, v1
	v_add_f32_e32 v98, 1.0, v98
	v_add_f32_e32 v99, 1.0, v99
	v_mul_f32_e32 v100, v91, v91
	v_rcp_f32_e32 v1, v1
	v_rcp_f32_e32 v98, v98
	v_rcp_f32_e32 v99, v99
	v_fma_f32 v100, v100, s99, v255
	v_mul_f32_e32 v100, v91, v100
	v_and_b32_e32 v105, 0xffff0000, v133
	v_lshlrev_b32_e32 v104, 16, v133
	v_pk_fma_f32 v[92:93], v[28:29], v[104:105], v[92:93]
	v_mul_f32_e32 v1, v94, v1
	v_mul_f32_e32 v94, v90, v98
	v_mul_f32_e32 v90, v95, v99
	v_mul_f32_e32 v98, v96, v96
	v_mul_f32_e32 v99, v92, v92
	v_exp_f32_e32 v100, v100
	v_fma_f32 v98, v98, s99, v255
	v_fma_f32 v99, v99, s99, v255
	v_mul_f32_e32 v98, v96, v98
	v_mul_f32_e32 v99, v92, v99
	v_add_f32_e32 v95, 1.0, v100
	v_rcp_f32_e32 v95, v95
	v_exp_f32_e32 v98, v98
	v_exp_f32_e32 v99, v99
	v_mul_f32_e32 v100, v93, v93
	v_mul_f32_e32 v95, v91, v95
	v_add_f32_e32 v91, 1.0, v98
	v_add_f32_e32 v98, 1.0, v99
	v_mul_f32_e32 v99, v97, v97
	v_fma_f32 v99, v99, s99, v255
	v_fma_f32 v100, v100, s99, v255
	v_mul_f32_e32 v99, v97, v99
	v_mul_f32_e32 v100, v93, v100
	v_exp_f32_e32 v99, v99
	v_exp_f32_e32 v100, v100
	v_rcp_f32_e32 v91, v91
	v_rcp_f32_e32 v98, v98
	v_add_f32_e32 v99, 1.0, v99
	v_add_f32_e32 v100, 1.0, v100
	v_rcp_f32_e32 v99, v99
	v_rcp_f32_e32 v100, v100
	v_mul_f32_e32 v91, v96, v91
	v_mul_f32_e32 v96, v92, v98
	v_mul_f32_e32 v92, v97, v99
	v_mul_f32_e32 v93, v93, v100
	v_cvt_pk_bf16_f32 v90, v1, v90
	v_cvt_pk_bf16_f32 v91, v91, v92
	v_cvt_pk_bf16_f32 v92, v94, v95
	v_cvt_pk_bf16_f32 v93, v96, v93
	global_store_dwordx4 v[110:111], v[90:93], off offset:256
	v_and_b32_e32 v97, 0xffff0000, v120
	v_lshlrev_b32_e32 v96, 16, v120
	v_and_b32_e32 v93, 0xffff0000, v118
	v_lshlrev_b32_e32 v92, 16, v118
	v_pk_fma_f32 v[86:87], v[30:31], v[92:93], v[86:87]
	v_pk_fma_f32 v[82:83], v[26:27], v[96:97], v[82:83]
	v_mul_f32_e32 v1, v86, v86
	v_mul_f32_e32 v92, v82, v82
	v_mul_f32_e32 v93, v87, v87
	v_fma_f32 v1, v1, s99, v255
	v_fma_f32 v92, v92, s99, v255
	v_fma_f32 v93, v93, s99, v255
	v_mul_f32_e32 v1, v86, v1
	v_mul_f32_e32 v92, v82, v92
	v_mul_f32_e32 v93, v87, v93
	v_exp_f32_e32 v1, v1
	v_exp_f32_e32 v92, v92
	v_exp_f32_e32 v93, v93
	v_and_b32_e32 v95, 0xffff0000, v119
	v_lshlrev_b32_e32 v94, 16, v119
	v_pk_fma_f32 v[88:89], v[32:33], v[94:95], v[88:89]
	v_add_f32_e32 v1, 1.0, v1
; __device__ __forceinline__ float gelu_tanh_f(float y) { const float t = 0.7978845608028654f * (y + 0.044715f * y * y * y); return y * fast_sigmoid(2.f * t); }
; __device__ __forceinline__ u32x4 pack8(const f32x4 v0, const f32x4 v1) { u32x4 w; w.x = pk_f16(v0[0], v0[1]); w.y = pk_f16(v0[2], v0[3]); w.z = pk_f16(v1[0], v1[1]); w.w = pk_f16(v1[2], v1[3]); return w; }
; __device__ __forceinline__ void unpack8(const u32x4 w, f32x4& v0, f32x4& v1) { v0 = (f32x4){f16lo(w.x), f16hi(w.x), f16lo(w.y), f16hi(w.y)}; v1 = (f32x4){f16lo(w.z), f16hi(w.z), f16lo(w.w), f16hi(w.w)}; }
;     __device__ __forceinline__ void operator()(AccRef acc, const Unit& u, int wr, int wc, int fr, int fq) const {
;     ...
;         for (int ai = 0; ai < 2; ++ai) { u32x4 uv[4][2];
; #pragma unroll
;             for (int m = 0; m < 4; ++m)
; #pragma unroll
;                 for (int bj = 0; bj < 2; ++bj) uv[m][bj] = *(const u32x4*)(Xg + (size_t)(row0 + ai * HALF + m * 16) * XK + bj * HALF);
;             __builtin_amdgcn_sched_barrier(0);
; #pragma unroll
;             for (int m = 0; m < 4; ++m)
; #pragma unroll
;                 for (int bj = 0; bj < 2; ++bj) { f32x4 u0, u1; unpack8(uv[m][bj], u0, u1);
;                     f32x4 v0 = acc[ai][bj][m][0] + d0 * u0, v1 = acc[ai][bj][m][1] + d1 * u1;
; #pragma unroll
;                     for (int j = 0; j < 4; ++j) { v0[j] = gelu_tanh_f(v0[j]); v1[j] = gelu_tanh_f(v1[j]); }
;                     *(u32x4*)(Yg + (size_t)(row0 + ai * HALF + m * 16) * 512 + bj * HALF) = pack8(v0, v1); } }
	v_add_f32_e32 v92, 1.0, v92
	v_add_f32_e32 v93, 1.0, v93
	v_mul_f32_e32 v94, v83, v83
	v_rcp_f32_e32 v1, v1
	v_rcp_f32_e32 v92, v92
	v_rcp_f32_e32 v93, v93
	v_fma_f32 v94, v94, s99, v255
	v_mul_f32_e32 v94, v83, v94
	v_and_b32_e32 v99, 0xffff0000, v121
	v_lshlrev_b32_e32 v98, 16, v121
	v_pk_fma_f32 v[84:85], v[28:29], v[98:99], v[84:85]
	v_mul_f32_e32 v1, v86, v1
	v_mul_f32_e32 v86, v82, v92
	v_mul_f32_e32 v82, v87, v93
	v_mul_f32_e32 v92, v88, v88
	v_mul_f32_e32 v93, v84, v84
	v_exp_f32_e32 v94, v94
	v_fma_f32 v92, v92, s99, v255
	v_fma_f32 v93, v93, s99, v255
	v_mul_f32_e32 v92, v88, v92
	v_mul_f32_e32 v93, v84, v93
	v_add_f32_e32 v87, 1.0, v94
	v_rcp_f32_e32 v87, v87
	v_exp_f32_e32 v92, v92
	v_exp_f32_e32 v93, v93
	v_mul_f32_e32 v94, v85, v85
	v_mul_f32_e32 v87, v83, v87
	v_add_f32_e32 v83, 1.0, v92
	v_add_f32_e32 v92, 1.0, v93
	v_mul_f32_e32 v93, v89, v89
	v_fma_f32 v93, v93, s99, v255
	v_fma_f32 v94, v94, s99, v255
	v_mul_f32_e32 v93, v89, v93
	v_mul_f32_e32 v94, v85, v94
	v_exp_f32_e32 v93, v93
	v_exp_f32_e32 v94, v94
	v_rcp_f32_e32 v83, v83
	v_rcp_f32_e32 v92, v92
	v_add_f32_e32 v93, 1.0, v93
	v_add_f32_e32 v94, 1.0, v94
	v_rcp_f32_e32 v93, v93
	v_rcp_f32_e32 v94, v94
	v_lshlrev_b64 v[90:91], 10, v[168:169]
	v_mul_f32_e32 v83, v88, v83
	v_mul_f32_e32 v88, v84, v92
	v_mul_f32_e32 v84, v89, v93
	v_mul_f32_e32 v85, v85, v94
	v_lshl_add_u64 v[90:91], v[162:163], 0, v[90:91]
	v_cvt_pk_bf16_f32 v82, v1, v82
	v_cvt_pk_bf16_f32 v83, v83, v84
	v_cvt_pk_bf16_f32 v84, v86, v87
	v_cvt_pk_bf16_f32 v85, v88, v85
	global_store_dwordx4 v[90:91], v[82:85], off
	v_and_b32_e32 v87, 0xffff0000, v108
	v_lshlrev_b32_e32 v86, 16, v108
	v_and_b32_e32 v83, 0xffff0000, v106
	v_lshlrev_b32_e32 v82, 16, v106
	v_pk_fma_f32 v[78:79], v[30:31], v[82:83], v[78:79]
	v_pk_fma_f32 v[74:75], v[26:27], v[86:87], v[74:75]
	v_mul_f32_e32 v1, v78, v78
	v_mul_f32_e32 v82, v74, v74
	v_mul_f32_e32 v83, v79, v79
	v_fma_f32 v1, v1, s99, v255
	v_fma_f32 v82, v82, s99, v255
	v_fma_f32 v83, v83, s99, v255
	v_mul_f32_e32 v1, v78, v1
	v_mul_f32_e32 v82, v74, v82
	v_mul_f32_e32 v83, v79, v83
	v_exp_f32_e32 v1, v1
	v_exp_f32_e32 v82, v82
	v_exp_f32_e32 v83, v83
	v_and_b32_e32 v85, 0xffff0000, v107
	v_lshlrev_b32_e32 v84, 16, v107
	v_pk_fma_f32 v[80:81], v[32:33], v[84:85], v[80:81]
	v_add_f32_e32 v1, 1.0, v1
	v_add_f32_e32 v82, 1.0, v82
	v_add_f32_e32 v83, 1.0, v83
	v_mul_f32_e32 v84, v75, v75
	v_rcp_f32_e32 v1, v1
	v_rcp_f32_e32 v82, v82
	v_rcp_f32_e32 v83, v83
	v_fma_f32 v84, v84, s99, v255
	v_mul_f32_e32 v84, v75, v84
	v_and_b32_e32 v89, 0xffff0000, v109
	v_lshlrev_b32_e32 v88, 16, v109
	v_pk_fma_f32 v[76:77], v[28:29], v[88:89], v[76:77]
	v_mul_f32_e32 v1, v78, v1
	v_mul_f32_e32 v78, v74, v82
	v_mul_f32_e32 v74, v79, v83
	v_mul_f32_e32 v82, v80, v80
	v_mul_f32_e32 v83, v76, v76
	v_exp_f32_e32 v84, v84
	v_fma_f32 v82, v82, s99, v255
	v_fma_f32 v83, v83, s99, v255
	v_mul_f32_e32 v82, v80, v82
	v_mul_f32_e32 v83, v76, v83
	v_add_f32_e32 v79, 1.0, v84
	v_rcp_f32_e32 v79, v79
	v_exp_f32_e32 v82, v82
	v_exp_f32_e32 v83, v83
	v_mul_f32_e32 v84, v77, v77
	v_mul_f32_e32 v79, v75, v79
	v_add_f32_e32 v75, 1.0, v82
	v_add_f32_e32 v82, 1.0, v83
	v_mul_f32_e32 v83, v81, v81
	v_fma_f32 v83, v83, s99, v255
	v_fma_f32 v84, v84, s99, v255
	v_mul_f32_e32 v83, v81, v83
	v_mul_f32_e32 v84, v77, v84
	v_exp_f32_e32 v83, v83
	v_exp_f32_e32 v84, v84
	v_rcp_f32_e32 v75, v75
	v_rcp_f32_e32 v82, v82
	v_add_f32_e32 v83, 1.0, v83
	v_add_f32_e32 v84, 1.0, v84
	v_rcp_f32_e32 v83, v83
	v_rcp_f32_e32 v84, v84
	v_mul_f32_e32 v75, v80, v75
	v_mul_f32_e32 v80, v76, v82
	v_mul_f32_e32 v76, v81, v83
	v_mul_f32_e32 v77, v77, v84
	v_cvt_pk_bf16_f32 v74, v1, v74
	v_cvt_pk_bf16_f32 v75, v75, v76
	v_cvt_pk_bf16_f32 v76, v78, v79
	v_cvt_pk_bf16_f32 v77, v80, v77
	v_add_u32_e32 v104, 0x80, v164
	global_store_dwordx4 v[90:91], v[74:77], off offset:256
	v_add_u32_e32 v102, 0x90, v164
	v_add_u32_e32 v100, 0xa0, v164
	v_mad_i64_i32 v[74:75], s[2:3], v104, s0, v[166:167]
	global_load_dwordx4 v[106:109], v[74:75], off offset:512
	global_load_dwordx4 v[110:113], v[74:75], off offset:768
	v_mad_i64_i32 v[74:75], s[2:3], v102, s0, v[166:167]
	v_add_u32_e32 v98, 0xb0, v164
	global_load_dwordx4 v[94:97], v[74:75], off offset:512
	global_load_dwordx4 v[90:93], v[74:75], off offset:768
	v_mad_i64_i32 v[74:75], s[2:3], v100, s0, v[166:167]
	v_mad_i64_i32 v[114:115], s[0:1], v98, s0, v[166:167]
	global_load_dwordx4 v[86:89], v[74:75], off offset:512
	global_load_dwordx4 v[82:85], v[74:75], off offset:768
	global_load_dwordx4 v[78:81], v[114:115], off offset:512
	s_nop 0
	global_load_dwordx4 v[74:77], v[114:115], off offset:768
	v_ashrrev_i32_e32 v105, 31, v104
	v_ashrrev_i32_e32 v103, 31, v102
	v_ashrrev_i32_e32 v101, 31, v100
	v_ashrrev_i32_e32 v99, 31, v98
	s_waitcnt vmcnt(7)
; __device__ __forceinline__ float gelu_tanh_f(float y) { const float t = 0.7978845608028654f * (y + 0.044715f * y * y * y); return y * fast_sigmoid(2.f * t); }
; __device__ __forceinline__ u32x4 pack8(const f32x4 v0, const f32x4 v1) { u32x4 w; w.x = pk_f16(v0[0], v0[1]); w.y = pk_f16(v0[2], v0[3]); w.z = pk_f16(v1[0], v1[1]); w.w = pk_f16(v1[2], v1[3]); return w; }
; __device__ __forceinline__ void unpack8(const u32x4 w, f32x4& v0, f32x4& v1) { v0 = (f32x4){f16lo(w.x), f16hi(w.x), f16lo(w.y), f16hi(w.y)}; v1 = (f32x4){f16lo(w.z), f16hi(w.z), f16lo(w.w), f16hi(w.w)}; }
;     __device__ __forceinline__ void operator()(AccRef acc, const Unit& u, int wr, int wc, int fr, int fq) const {
;     ...
;             for (int m = 0; m < 4; ++m)
; #pragma unroll
;                 for (int bj = 0; bj < 2; ++bj) { f32x4 u0, u1; unpack8(uv[m][bj], u0, u1);
;                     f32x4 v0 = acc[ai][bj][m][0] + d0 * u0, v1 = acc[ai][bj][m][1] + d1 * u1;
; #pragma unroll
;                     for (int j = 0; j < 4; ++j) { v0[j] = gelu_tanh_f(v0[j]); v1[j] = gelu_tanh_f(v1[j]); }
;                     *(u32x4*)(Yg + (size_t)(row0 + ai * HALF + m * 16) * 512 + bj * HALF) = pack8(v0, v1); } }
	v_and_b32_e32 v115, 0xffff0000, v106
	v_lshlrev_b32_e32 v114, 16, v106
	v_and_b32_e32 v117, 0xffff0000, v107
	v_lshlrev_b32_e32 v116, 16, v107
	v_and_b32_e32 v107, 0xffff0000, v108
	v_lshlrev_b32_e32 v106, 16, v108
	v_pk_fma_f32 v[70:71], v[30:31], v[114:115], v[70:71]
	v_pk_fma_f32 v[66:67], v[26:27], v[106:107], v[66:67]
	v_mul_f32_e32 v1, v70, v70
	v_mul_f32_e32 v106, v66, v66
	v_mul_f32_e32 v107, v71, v71
	v_fma_f32 v1, v1, s99, v255
	v_fma_f32 v106, v106, s99, v255
	v_fma_f32 v107, v107, s99, v255
	v_mul_f32_e32 v1, v70, v1
	v_mul_f32_e32 v106, v66, v106
	v_mul_f32_e32 v107, v71, v107
	v_exp_f32_e32 v1, v1
	v_exp_f32_e32 v106, v106
	v_exp_f32_e32 v107, v107
	v_mul_f32_e32 v108, v67, v67
	v_add_f32_e32 v1, 1.0, v1
	v_add_f32_e32 v106, 1.0, v106
	v_add_f32_e32 v107, 1.0, v107
	v_rcp_f32_e32 v1, v1
	v_rcp_f32_e32 v106, v106
	v_rcp_f32_e32 v107, v107
	v_fma_f32 v108, v108, s99, v255
	v_mul_f32_e32 v108, v67, v108
	v_and_b32_e32 v119, 0xffff0000, v109
	v_lshlrev_b32_e32 v118, 16, v109
	v_pk_fma_f32 v[72:73], v[32:33], v[116:117], v[72:73]
	v_pk_fma_f32 v[68:69], v[28:29], v[118:119], v[68:69]
	v_mul_f32_e32 v1, v70, v1
	v_mul_f32_e32 v70, v66, v106
	v_mul_f32_e32 v66, v71, v107
	v_mul_f32_e32 v106, v72, v72
	v_mul_f32_e32 v107, v68, v68
	v_exp_f32_e32 v108, v108
	v_fma_f32 v106, v106, s99, v255
	v_fma_f32 v107, v107, s99, v255
	v_mul_f32_e32 v106, v72, v106
	v_mul_f32_e32 v107, v68, v107
	v_add_f32_e32 v71, 1.0, v108
	v_rcp_f32_e32 v71, v71
	v_exp_f32_e32 v106, v106
	v_exp_f32_e32 v107, v107
	v_mul_f32_e32 v108, v69, v69
	v_mul_f32_e32 v71, v67, v71
	v_add_f32_e32 v67, 1.0, v106
	v_add_f32_e32 v106, 1.0, v107
	v_mul_f32_e32 v107, v73, v73
	v_fma_f32 v107, v107, s99, v255
	v_fma_f32 v108, v108, s99, v255
	v_mul_f32_e32 v107, v73, v107
	v_mul_f32_e32 v108, v69, v108
	v_exp_f32_e32 v107, v107
	v_exp_f32_e32 v108, v108
	v_rcp_f32_e32 v67, v67
	v_rcp_f32_e32 v106, v106
	v_add_f32_e32 v107, 1.0, v107
	v_add_f32_e32 v108, 1.0, v108
	v_rcp_f32_e32 v107, v107
	v_rcp_f32_e32 v108, v108
	v_lshlrev_b64 v[104:105], 10, v[104:105]
	v_mul_f32_e32 v67, v72, v67
	v_mul_f32_e32 v72, v68, v106
	v_mul_f32_e32 v68, v73, v107
	v_mul_f32_e32 v69, v69, v108
	v_lshl_add_u64 v[104:105], v[162:163], 0, v[104:105]
	v_cvt_pk_bf16_f32 v66, v1, v66
	v_cvt_pk_bf16_f32 v67, v67, v68
	v_cvt_pk_bf16_f32 v68, v70, v71
	v_cvt_pk_bf16_f32 v69, v72, v69
	global_store_dwordx4 v[104:105], v[66:69], off
	s_waitcnt vmcnt(7)
	v_and_b32_e32 v71, 0xffff0000, v112
	v_lshlrev_b32_e32 v70, 16, v112
	v_and_b32_e32 v67, 0xffff0000, v110
	v_lshlrev_b32_e32 v66, 16, v110
	v_pk_fma_f32 v[62:63], v[30:31], v[66:67], v[62:63]
	v_pk_fma_f32 v[58:59], v[26:27], v[70:71], v[58:59]
	v_mul_f32_e32 v1, v62, v62
	v_mul_f32_e32 v66, v58, v58
	v_mul_f32_e32 v67, v63, v63
	v_fma_f32 v1, v1, s99, v255
	v_fma_f32 v66, v66, s99, v255
	v_fma_f32 v67, v67, s99, v255
	v_mul_f32_e32 v1, v62, v1
	v_mul_f32_e32 v66, v58, v66
	v_mul_f32_e32 v67, v63, v67
	v_exp_f32_e32 v1, v1
	v_exp_f32_e32 v66, v66
	v_exp_f32_e32 v67, v67
	v_and_b32_e32 v69, 0xffff0000, v111
	v_lshlrev_b32_e32 v68, 16, v111
	v_pk_fma_f32 v[64:65], v[32:33], v[68:69], v[64:65]
	v_add_f32_e32 v1, 1.0, v1
	v_add_f32_e32 v66, 1.0, v66
	v_add_f32_e32 v67, 1.0, v67
	v_mul_f32_e32 v68, v59, v59
	v_rcp_f32_e32 v1, v1
	v_rcp_f32_e32 v66, v66
	v_rcp_f32_e32 v67, v67
	v_fma_f32 v68, v68, s99, v255
	v_mul_f32_e32 v68, v59, v68
	v_and_b32_e32 v73, 0xffff0000, v113
	v_lshlrev_b32_e32 v72, 16, v113
	v_pk_fma_f32 v[60:61], v[28:29], v[72:73], v[60:61]
	v_mul_f32_e32 v1, v62, v1
	v_mul_f32_e32 v62, v58, v66
	v_mul_f32_e32 v58, v63, v67
	v_mul_f32_e32 v66, v64, v64
	v_mul_f32_e32 v67, v60, v60
	v_exp_f32_e32 v68, v68
	v_fma_f32 v66, v66, s99, v255
	v_fma_f32 v67, v67, s99, v255
	v_mul_f32_e32 v66, v64, v66
	v_mul_f32_e32 v67, v60, v67
	v_add_f32_e32 v63, 1.0, v68
	v_rcp_f32_e32 v63, v63
	v_exp_f32_e32 v66, v66
	v_exp_f32_e32 v67, v67
	v_mul_f32_e32 v68, v61, v61
	v_mul_f32_e32 v63, v59, v63
	v_add_f32_e32 v59, 1.0, v66
	v_add_f32_e32 v66, 1.0, v67
	v_mul_f32_e32 v67, v65, v65
	v_fma_f32 v67, v67, s99, v255
	v_fma_f32 v68, v68, s99, v255
	v_mul_f32_e32 v67, v65, v67
	v_mul_f32_e32 v68, v61, v68
	v_exp_f32_e32 v67, v67
	v_exp_f32_e32 v68, v68
	v_rcp_f32_e32 v59, v59
	v_rcp_f32_e32 v66, v66
	v_add_f32_e32 v67, 1.0, v67
	v_add_f32_e32 v68, 1.0, v68
	v_rcp_f32_e32 v67, v67
	v_rcp_f32_e32 v68, v68
	v_mul_f32_e32 v59, v64, v59
	v_mul_f32_e32 v64, v60, v66
	v_mul_f32_e32 v60, v65, v67
	v_mul_f32_e32 v61, v61, v68
	v_cvt_pk_bf16_f32 v58, v1, v58
	v_cvt_pk_bf16_f32 v59, v59, v60
	v_cvt_pk_bf16_f32 v60, v62, v63
	v_cvt_pk_bf16_f32 v61, v64, v61
	global_store_dwordx4 v[104:105], v[58:61], off offset:256
	s_waitcnt vmcnt(7)
; __device__ __forceinline__ float gelu_tanh_f(float y) { const float t = 0.7978845608028654f * (y + 0.044715f * y * y * y); return y * fast_sigmoid(2.f * t); }
; __device__ __forceinline__ u32x4 pack8(const f32x4 v0, const f32x4 v1) { u32x4 w; w.x = pk_f16(v0[0], v0[1]); w.y = pk_f16(v0[2], v0[3]); w.z = pk_f16(v1[0], v1[1]); w.w = pk_f16(v1[2], v1[3]); return w; }
; __device__ __forceinline__ void unpack8(const u32x4 w, f32x4& v0, f32x4& v1) { v0 = (f32x4){f16lo(w.x), f16hi(w.x), f16lo(w.y), f16hi(w.y)}; v1 = (f32x4){f16lo(w.z), f16hi(w.z), f16lo(w.w), f16hi(w.w)}; }
;     __device__ __forceinline__ void operator()(AccRef acc, const Unit& u, int wr, int wc, int fr, int fq) const {
;     ...
;             for (int m = 0; m < 4; ++m)
; #pragma unroll
;                 for (int bj = 0; bj < 2; ++bj) { f32x4 u0, u1; unpack8(uv[m][bj], u0, u1);
;                     f32x4 v0 = acc[ai][bj][m][0] + d0 * u0, v1 = acc[ai][bj][m][1] + d1 * u1;
; #pragma unroll
;                     for (int j = 0; j < 4; ++j) { v0[j] = gelu_tanh_f(v0[j]); v1[j] = gelu_tanh_f(v1[j]); }
;                     *(u32x4*)(Yg + (size_t)(row0 + ai * HALF + m * 16) * 512 + bj * HALF) = pack8(v0, v1); } }
	v_and_b32_e32 v65, 0xffff0000, v96
	v_lshlrev_b32_e32 v64, 16, v96
	v_and_b32_e32 v61, 0xffff0000, v94
	v_lshlrev_b32_e32 v60, 16, v94
	v_pk_fma_f32 v[54:55], v[30:31], v[60:61], v[54:55]
	v_pk_fma_f32 v[50:51], v[26:27], v[64:65], v[50:51]
	v_mul_f32_e32 v1, v54, v54
	v_mul_f32_e32 v60, v50, v50
	v_mul_f32_e32 v61, v55, v55
	v_fma_f32 v1, v1, s99, v255
	v_fma_f32 v60, v60, s99, v255
	v_fma_f32 v61, v61, s99, v255
	v_mul_f32_e32 v1, v54, v1
	v_mul_f32_e32 v60, v50, v60
	v_mul_f32_e32 v61, v55, v61
	v_exp_f32_e32 v1, v1
	v_exp_f32_e32 v60, v60
	v_exp_f32_e32 v61, v61
	v_and_b32_e32 v63, 0xffff0000, v95
	v_lshlrev_b32_e32 v62, 16, v95
	v_pk_fma_f32 v[56:57], v[32:33], v[62:63], v[56:57]
	v_add_f32_e32 v1, 1.0, v1
	v_add_f32_e32 v60, 1.0, v60
	v_add_f32_e32 v61, 1.0, v61
	v_mul_f32_e32 v62, v51, v51
	v_rcp_f32_e32 v1, v1
	v_rcp_f32_e32 v60, v60
	v_rcp_f32_e32 v61, v61
	v_fma_f32 v62, v62, s99, v255
	v_mul_f32_e32 v62, v51, v62
	v_and_b32_e32 v67, 0xffff0000, v97
	v_lshlrev_b32_e32 v66, 16, v97
	v_pk_fma_f32 v[52:53], v[28:29], v[66:67], v[52:53]
	v_mul_f32_e32 v1, v54, v1
	v_mul_f32_e32 v54, v50, v60
	v_mul_f32_e32 v50, v55, v61
	v_mul_f32_e32 v60, v56, v56
	v_mul_f32_e32 v61, v52, v52
	v_exp_f32_e32 v62, v62
	v_fma_f32 v60, v60, s99, v255
	v_fma_f32 v61, v61, s99, v255
	v_mul_f32_e32 v60, v56, v60
	v_mul_f32_e32 v61, v52, v61
	v_add_f32_e32 v55, 1.0, v62
	v_rcp_f32_e32 v55, v55
	v_exp_f32_e32 v60, v60
	v_exp_f32_e32 v61, v61
	v_mul_f32_e32 v62, v53, v53
	v_mul_f32_e32 v55, v51, v55
	v_add_f32_e32 v51, 1.0, v60
	v_add_f32_e32 v60, 1.0, v61
	v_mul_f32_e32 v61, v57, v57
	v_fma_f32 v61, v61, s99, v255
	v_fma_f32 v62, v62, s99, v255
	v_mul_f32_e32 v61, v57, v61
	v_mul_f32_e32 v62, v53, v62
	v_exp_f32_e32 v61, v61
	v_exp_f32_e32 v62, v62
	v_rcp_f32_e32 v51, v51
	v_rcp_f32_e32 v60, v60
	v_add_f32_e32 v61, 1.0, v61
	v_add_f32_e32 v62, 1.0, v62
	v_rcp_f32_e32 v61, v61
	v_rcp_f32_e32 v62, v62
	v_lshlrev_b64 v[58:59], 10, v[102:103]
	v_mul_f32_e32 v51, v56, v51
	v_mul_f32_e32 v56, v52, v60
	v_mul_f32_e32 v52, v57, v61
	v_mul_f32_e32 v53, v53, v62
	v_lshl_add_u64 v[58:59], v[162:163], 0, v[58:59]
	v_cvt_pk_bf16_f32 v50, v1, v50
	v_cvt_pk_bf16_f32 v51, v51, v52
	v_cvt_pk_bf16_f32 v52, v54, v55
	v_cvt_pk_bf16_f32 v53, v56, v53
	global_store_dwordx4 v[58:59], v[50:53], off
	s_waitcnt vmcnt(7)
	v_and_b32_e32 v55, 0xffff0000, v92
	v_lshlrev_b32_e32 v54, 16, v92
	v_and_b32_e32 v51, 0xffff0000, v90
	v_lshlrev_b32_e32 v50, 16, v90
	v_pk_fma_f32 v[46:47], v[30:31], v[50:51], v[46:47]
	v_pk_fma_f32 v[42:43], v[26:27], v[54:55], v[42:43]
	v_mul_f32_e32 v1, v46, v46
	v_mul_f32_e32 v50, v42, v42
	v_mul_f32_e32 v51, v47, v47
	v_fma_f32 v1, v1, s99, v255
	v_fma_f32 v50, v50, s99, v255
	v_fma_f32 v51, v51, s99, v255
	v_mul_f32_e32 v1, v46, v1
	v_mul_f32_e32 v50, v42, v50
	v_mul_f32_e32 v51, v47, v51
	v_exp_f32_e32 v1, v1
	v_exp_f32_e32 v50, v50
	v_exp_f32_e32 v51, v51
	v_and_b32_e32 v53, 0xffff0000, v91
	v_lshlrev_b32_e32 v52, 16, v91
	v_pk_fma_f32 v[48:49], v[32:33], v[52:53], v[48:49]
	v_add_f32_e32 v1, 1.0, v1
	v_add_f32_e32 v50, 1.0, v50
	v_add_f32_e32 v51, 1.0, v51
	v_mul_f32_e32 v52, v43, v43
	v_rcp_f32_e32 v1, v1
	v_rcp_f32_e32 v50, v50
	v_rcp_f32_e32 v51, v51
	v_fma_f32 v52, v52, s99, v255
	v_mul_f32_e32 v52, v43, v52
	v_and_b32_e32 v57, 0xffff0000, v93
	v_lshlrev_b32_e32 v56, 16, v93
	v_pk_fma_f32 v[44:45], v[28:29], v[56:57], v[44:45]
	v_mul_f32_e32 v1, v46, v1
	v_mul_f32_e32 v46, v42, v50
	v_mul_f32_e32 v42, v47, v51
	v_mul_f32_e32 v50, v48, v48
	v_mul_f32_e32 v51, v44, v44
	v_exp_f32_e32 v52, v52
	v_fma_f32 v50, v50, s99, v255
	v_fma_f32 v51, v51, s99, v255
	v_mul_f32_e32 v50, v48, v50
	v_mul_f32_e32 v51, v44, v51
	v_add_f32_e32 v47, 1.0, v52
	v_rcp_f32_e32 v47, v47
	v_exp_f32_e32 v50, v50
	v_exp_f32_e32 v51, v51
	v_mul_f32_e32 v52, v45, v45
	v_mul_f32_e32 v47, v43, v47
	v_add_f32_e32 v43, 1.0, v50
	v_add_f32_e32 v50, 1.0, v51
	v_mul_f32_e32 v51, v49, v49
	v_fma_f32 v51, v51, s99, v255
	v_fma_f32 v52, v52, s99, v255
	v_mul_f32_e32 v51, v49, v51
	v_mul_f32_e32 v52, v45, v52
	v_exp_f32_e32 v51, v51
	v_exp_f32_e32 v52, v52
	v_rcp_f32_e32 v43, v43
	v_rcp_f32_e32 v50, v50
	v_add_f32_e32 v51, 1.0, v51
	v_add_f32_e32 v52, 1.0, v52
	v_rcp_f32_e32 v51, v51
	v_rcp_f32_e32 v52, v52
	v_mul_f32_e32 v43, v48, v43
	v_mul_f32_e32 v48, v44, v50
	v_mul_f32_e32 v44, v49, v51
	v_mul_f32_e32 v45, v45, v52
	v_cvt_pk_bf16_f32 v42, v1, v42
	v_cvt_pk_bf16_f32 v43, v43, v44
	v_cvt_pk_bf16_f32 v44, v46, v47
	v_cvt_pk_bf16_f32 v45, v48, v45
	global_store_dwordx4 v[58:59], v[42:45], off offset:256
	s_waitcnt vmcnt(7)
; __device__ __forceinline__ float gelu_tanh_f(float y) { const float t = 0.7978845608028654f * (y + 0.044715f * y * y * y); return y * fast_sigmoid(2.f * t); }
; __device__ __forceinline__ u32x4 pack8(const f32x4 v0, const f32x4 v1) { u32x4 w; w.x = pk_f16(v0[0], v0[1]); w.y = pk_f16(v0[2], v0[3]); w.z = pk_f16(v1[0], v1[1]); w.w = pk_f16(v1[2], v1[3]); return w; }
; __device__ __forceinline__ void unpack8(const u32x4 w, f32x4& v0, f32x4& v1) { v0 = (f32x4){f16lo(w.x), f16hi(w.x), f16lo(w.y), f16hi(w.y)}; v1 = (f32x4){f16lo(w.z), f16hi(w.z), f16lo(w.w), f16hi(w.w)}; }
;     __device__ __forceinline__ void operator()(AccRef acc, const Unit& u, int wr, int wc, int fr, int fq) const {
;     ...
;             for (int m = 0; m < 4; ++m)
; #pragma unroll
;                 for (int bj = 0; bj < 2; ++bj) { f32x4 u0, u1; unpack8(uv[m][bj], u0, u1);
;                     f32x4 v0 = acc[ai][bj][m][0] + d0 * u0, v1 = acc[ai][bj][m][1] + d1 * u1;
; #pragma unroll
;                     for (int j = 0; j < 4; ++j) { v0[j] = gelu_tanh_f(v0[j]); v1[j] = gelu_tanh_f(v1[j]); }
;                     *(u32x4*)(Yg + (size_t)(row0 + ai * HALF + m * 16) * 512 + bj * HALF) = pack8(v0, v1); } }
	v_and_b32_e32 v49, 0xffff0000, v88
	v_lshlrev_b32_e32 v48, 16, v88
	v_and_b32_e32 v45, 0xffff0000, v86
	v_lshlrev_b32_e32 v44, 16, v86
	v_pk_fma_f32 v[38:39], v[30:31], v[44:45], v[38:39]
	v_pk_fma_f32 v[34:35], v[26:27], v[48:49], v[34:35]
	v_mul_f32_e32 v1, v38, v38
	v_mul_f32_e32 v44, v34, v34
	v_mul_f32_e32 v45, v39, v39
	v_fma_f32 v1, v1, s99, v255
	v_fma_f32 v44, v44, s99, v255
	v_fma_f32 v45, v45, s99, v255
	v_mul_f32_e32 v1, v38, v1
	v_mul_f32_e32 v44, v34, v44
	v_mul_f32_e32 v45, v39, v45
	v_exp_f32_e32 v1, v1
	v_exp_f32_e32 v44, v44
	v_exp_f32_e32 v45, v45
	v_and_b32_e32 v47, 0xffff0000, v87
	v_lshlrev_b32_e32 v46, 16, v87
	v_pk_fma_f32 v[40:41], v[32:33], v[46:47], v[40:41]
	v_add_f32_e32 v1, 1.0, v1
	v_add_f32_e32 v44, 1.0, v44
	v_add_f32_e32 v45, 1.0, v45
	v_mul_f32_e32 v46, v35, v35
	v_rcp_f32_e32 v1, v1
	v_rcp_f32_e32 v44, v44
	v_rcp_f32_e32 v45, v45
	v_fma_f32 v46, v46, s99, v255
	v_mul_f32_e32 v46, v35, v46
	v_and_b32_e32 v51, 0xffff0000, v89
	v_lshlrev_b32_e32 v50, 16, v89
	v_pk_fma_f32 v[36:37], v[28:29], v[50:51], v[36:37]
	v_mul_f32_e32 v1, v38, v1
	v_mul_f32_e32 v38, v34, v44
	v_mul_f32_e32 v34, v39, v45
	v_mul_f32_e32 v44, v40, v40
	v_mul_f32_e32 v45, v36, v36
	v_exp_f32_e32 v46, v46
	v_fma_f32 v44, v44, s99, v255
	v_fma_f32 v45, v45, s99, v255
	v_mul_f32_e32 v44, v40, v44
	v_mul_f32_e32 v45, v36, v45
	v_add_f32_e32 v39, 1.0, v46
	v_rcp_f32_e32 v39, v39
	v_exp_f32_e32 v44, v44
	v_exp_f32_e32 v45, v45
	v_mul_f32_e32 v46, v37, v37
	v_mul_f32_e32 v39, v35, v39
	v_add_f32_e32 v35, 1.0, v44
	v_add_f32_e32 v44, 1.0, v45
	v_mul_f32_e32 v45, v41, v41
	v_fma_f32 v45, v45, s99, v255
	v_fma_f32 v46, v46, s99, v255
	v_mul_f32_e32 v45, v41, v45
	v_mul_f32_e32 v46, v37, v46
	v_exp_f32_e32 v45, v45
	v_exp_f32_e32 v46, v46
	v_rcp_f32_e32 v35, v35
	v_rcp_f32_e32 v44, v44
	v_add_f32_e32 v45, 1.0, v45
	v_add_f32_e32 v46, 1.0, v46
	v_rcp_f32_e32 v45, v45
	v_rcp_f32_e32 v46, v46
	v_lshlrev_b64 v[42:43], 10, v[100:101]
	v_mul_f32_e32 v35, v40, v35
	v_mul_f32_e32 v40, v36, v44
	v_mul_f32_e32 v36, v41, v45
	v_mul_f32_e32 v37, v37, v46
	v_lshl_add_u64 v[42:43], v[162:163], 0, v[42:43]
	v_cvt_pk_bf16_f32 v34, v1, v34
	v_cvt_pk_bf16_f32 v35, v35, v36
	v_cvt_pk_bf16_f32 v36, v38, v39
	v_cvt_pk_bf16_f32 v37, v40, v37
	global_store_dwordx4 v[42:43], v[34:37], off
	s_waitcnt vmcnt(7)
	v_and_b32_e32 v39, 0xffff0000, v84
	v_lshlrev_b32_e32 v38, 16, v84
	v_and_b32_e32 v35, 0xffff0000, v82
	v_lshlrev_b32_e32 v34, 16, v82
	v_pk_fma_f32 v[22:23], v[30:31], v[34:35], v[22:23]
	v_pk_fma_f32 v[18:19], v[26:27], v[38:39], v[18:19]
	v_mul_f32_e32 v1, v22, v22
	v_mul_f32_e32 v34, v18, v18
	v_mul_f32_e32 v35, v23, v23
	v_fma_f32 v1, v1, s99, v255
	v_fma_f32 v34, v34, s99, v255
	v_fma_f32 v35, v35, s99, v255
	v_mul_f32_e32 v1, v22, v1
	v_mul_f32_e32 v34, v18, v34
	v_mul_f32_e32 v35, v23, v35
	v_exp_f32_e32 v1, v1
	v_exp_f32_e32 v34, v34
	v_exp_f32_e32 v35, v35
	v_and_b32_e32 v37, 0xffff0000, v83
	v_lshlrev_b32_e32 v36, 16, v83
	v_pk_fma_f32 v[24:25], v[32:33], v[36:37], v[24:25]
	v_add_f32_e32 v1, 1.0, v1
	v_add_f32_e32 v34, 1.0, v34
	v_add_f32_e32 v35, 1.0, v35
	v_mul_f32_e32 v36, v19, v19
	v_rcp_f32_e32 v1, v1
	v_rcp_f32_e32 v34, v34
	v_rcp_f32_e32 v35, v35
	v_fma_f32 v36, v36, s99, v255
	v_mul_f32_e32 v36, v19, v36
	v_and_b32_e32 v41, 0xffff0000, v85
	v_lshlrev_b32_e32 v40, 16, v85
	v_pk_fma_f32 v[20:21], v[28:29], v[40:41], v[20:21]
	v_mul_f32_e32 v1, v22, v1
	v_mul_f32_e32 v22, v18, v34
	v_mul_f32_e32 v18, v23, v35
	v_mul_f32_e32 v34, v24, v24
	v_mul_f32_e32 v35, v20, v20
	v_exp_f32_e32 v36, v36
	v_fma_f32 v34, v34, s99, v255
	v_fma_f32 v35, v35, s99, v255
	v_mul_f32_e32 v34, v24, v34
	v_mul_f32_e32 v35, v20, v35
	v_add_f32_e32 v23, 1.0, v36
	v_rcp_f32_e32 v23, v23
	v_exp_f32_e32 v34, v34
	v_exp_f32_e32 v35, v35
	v_mul_f32_e32 v36, v21, v21
	v_mul_f32_e32 v23, v19, v23
	v_add_f32_e32 v19, 1.0, v34
	v_add_f32_e32 v34, 1.0, v35
	v_mul_f32_e32 v35, v25, v25
	v_fma_f32 v35, v35, s99, v255
	v_fma_f32 v36, v36, s99, v255
	v_mul_f32_e32 v35, v25, v35
	v_mul_f32_e32 v36, v21, v36
	v_exp_f32_e32 v35, v35
	v_exp_f32_e32 v36, v36
	v_rcp_f32_e32 v19, v19
	v_rcp_f32_e32 v34, v34
	v_add_f32_e32 v35, 1.0, v35
	v_add_f32_e32 v36, 1.0, v36
	v_rcp_f32_e32 v35, v35
	v_rcp_f32_e32 v36, v36
	v_mul_f32_e32 v19, v24, v19
	v_mul_f32_e32 v24, v20, v34
	v_mul_f32_e32 v20, v25, v35
	v_mul_f32_e32 v21, v21, v36
	v_cvt_pk_bf16_f32 v18, v1, v18
	v_cvt_pk_bf16_f32 v19, v19, v20
	v_cvt_pk_bf16_f32 v20, v22, v23
	v_cvt_pk_bf16_f32 v21, v24, v21
	global_store_dwordx4 v[42:43], v[18:21], off offset:256
	s_waitcnt vmcnt(7)
; __device__ __forceinline__ float gelu_tanh_f(float y) { const float t = 0.7978845608028654f * (y + 0.044715f * y * y * y); return y * fast_sigmoid(2.f * t); }
; __device__ __forceinline__ u32x4 pack8(const f32x4 v0, const f32x4 v1) { u32x4 w; w.x = pk_f16(v0[0], v0[1]); w.y = pk_f16(v0[2], v0[3]); w.z = pk_f16(v1[0], v1[1]); w.w = pk_f16(v1[2], v1[3]); return w; }
; __device__ __forceinline__ void unpack8(const u32x4 w, f32x4& v0, f32x4& v1) { v0 = (f32x4){f16lo(w.x), f16hi(w.x), f16lo(w.y), f16hi(w.y)}; v1 = (f32x4){f16lo(w.z), f16hi(w.z), f16lo(w.w), f16hi(w.w)}; }
;     __device__ __forceinline__ void operator()(AccRef acc, const Unit& u, int wr, int wc, int fr, int fq) const {
;     ...
;             for (int m = 0; m < 4; ++m)
; #pragma unroll
;                 for (int bj = 0; bj < 2; ++bj) { f32x4 u0, u1; unpack8(uv[m][bj], u0, u1);
;                     f32x4 v0 = acc[ai][bj][m][0] + d0 * u0, v1 = acc[ai][bj][m][1] + d1 * u1;
; #pragma unroll
;                     for (int j = 0; j < 4; ++j) { v0[j] = gelu_tanh_f(v0[j]); v1[j] = gelu_tanh_f(v1[j]); }
;                     *(u32x4*)(Yg + (size_t)(row0 + ai * HALF + m * 16) * 512 + bj * HALF) = pack8(v0, v1); } }
	v_and_b32_e32 v25, 0xffff0000, v80
	v_lshlrev_b32_e32 v24, 16, v80
	v_and_b32_e32 v21, 0xffff0000, v78
	v_lshlrev_b32_e32 v20, 16, v78
	v_pk_fma_f32 v[14:15], v[30:31], v[20:21], v[14:15]
	v_pk_fma_f32 v[10:11], v[26:27], v[24:25], v[10:11]
	v_mul_f32_e32 v1, v14, v14
	v_mul_f32_e32 v20, v10, v10
	v_mul_f32_e32 v21, v15, v15
	v_fma_f32 v1, v1, s99, v255
	v_fma_f32 v20, v20, s99, v255
	v_fma_f32 v21, v21, s99, v255
	v_mul_f32_e32 v1, v14, v1
	v_mul_f32_e32 v20, v10, v20
	v_mul_f32_e32 v21, v15, v21
	v_exp_f32_e32 v1, v1
	v_exp_f32_e32 v20, v20
	v_exp_f32_e32 v21, v21
	v_and_b32_e32 v23, 0xffff0000, v79
	v_lshlrev_b32_e32 v22, 16, v79
	v_pk_fma_f32 v[16:17], v[32:33], v[22:23], v[16:17]
	v_add_f32_e32 v1, 1.0, v1
	v_add_f32_e32 v20, 1.0, v20
	v_add_f32_e32 v21, 1.0, v21
	v_mul_f32_e32 v22, v11, v11
	v_rcp_f32_e32 v1, v1
	v_rcp_f32_e32 v20, v20
	v_rcp_f32_e32 v21, v21
	v_fma_f32 v22, v22, s99, v255
	v_mul_f32_e32 v22, v11, v22
	v_and_b32_e32 v35, 0xffff0000, v81
	v_lshlrev_b32_e32 v34, 16, v81
	v_pk_fma_f32 v[12:13], v[28:29], v[34:35], v[12:13]
	v_mul_f32_e32 v1, v14, v1
	v_mul_f32_e32 v14, v10, v20
	v_mul_f32_e32 v10, v15, v21
	v_mul_f32_e32 v20, v16, v16
	v_mul_f32_e32 v21, v12, v12
	v_exp_f32_e32 v22, v22
	v_fma_f32 v20, v20, s99, v255
	v_fma_f32 v21, v21, s99, v255
	v_mul_f32_e32 v20, v16, v20
	v_mul_f32_e32 v21, v12, v21
	v_add_f32_e32 v15, 1.0, v22
	v_rcp_f32_e32 v15, v15
	v_exp_f32_e32 v20, v20
	v_exp_f32_e32 v21, v21
	v_mul_f32_e32 v22, v13, v13
	v_mul_f32_e32 v15, v11, v15
	v_add_f32_e32 v11, 1.0, v20
	v_add_f32_e32 v20, 1.0, v21
	v_mul_f32_e32 v21, v17, v17
	v_fma_f32 v21, v21, s99, v255
	v_fma_f32 v22, v22, s99, v255
	v_mul_f32_e32 v21, v17, v21
	v_mul_f32_e32 v22, v13, v22
	v_exp_f32_e32 v21, v21
	v_exp_f32_e32 v22, v22
	v_rcp_f32_e32 v11, v11
	v_rcp_f32_e32 v20, v20
	v_add_f32_e32 v21, 1.0, v21
	v_add_f32_e32 v22, 1.0, v22
	v_rcp_f32_e32 v21, v21
	v_rcp_f32_e32 v22, v22
	v_lshlrev_b64 v[18:19], 10, v[98:99]
	v_mul_f32_e32 v11, v16, v11
	v_mul_f32_e32 v16, v12, v20
	v_mul_f32_e32 v12, v17, v21
	v_mul_f32_e32 v13, v13, v22
	v_lshl_add_u64 v[18:19], v[162:163], 0, v[18:19]
	v_cvt_pk_bf16_f32 v10, v1, v10
	v_cvt_pk_bf16_f32 v11, v11, v12
	v_cvt_pk_bf16_f32 v12, v14, v15
	v_cvt_pk_bf16_f32 v13, v16, v13
	global_store_dwordx4 v[18:19], v[10:13], off
	s_waitcnt vmcnt(7)
	v_and_b32_e32 v15, 0xffff0000, v76
	v_lshlrev_b32_e32 v14, 16, v76
	v_and_b32_e32 v11, 0xffff0000, v74
	v_lshlrev_b32_e32 v10, 16, v74
	v_pk_fma_f32 v[6:7], v[30:31], v[10:11], v[6:7]
	v_pk_fma_f32 v[2:3], v[26:27], v[14:15], v[2:3]
	v_mul_f32_e32 v1, v6, v6
	v_mul_f32_e32 v10, v2, v2
	v_mul_f32_e32 v11, v7, v7
	v_fma_f32 v1, v1, s99, v255
	v_fma_f32 v10, v10, s99, v255
	v_fma_f32 v11, v11, s99, v255
	v_mul_f32_e32 v1, v6, v1
	v_mul_f32_e32 v10, v2, v10
	v_mul_f32_e32 v11, v7, v11
	v_exp_f32_e32 v1, v1
	v_exp_f32_e32 v10, v10
	v_exp_f32_e32 v11, v11
	v_and_b32_e32 v13, 0xffff0000, v75
	v_lshlrev_b32_e32 v12, 16, v75
	v_pk_fma_f32 v[8:9], v[32:33], v[12:13], v[8:9]
	v_add_f32_e32 v1, 1.0, v1
	v_add_f32_e32 v10, 1.0, v10
	v_add_f32_e32 v11, 1.0, v11
	v_mul_f32_e32 v12, v3, v3
	v_rcp_f32_e32 v1, v1
	v_rcp_f32_e32 v10, v10
	v_rcp_f32_e32 v11, v11
	v_fma_f32 v12, v12, s99, v255
	v_mul_f32_e32 v12, v3, v12
	v_and_b32_e32 v17, 0xffff0000, v77
	v_lshlrev_b32_e32 v16, 16, v77
	v_pk_fma_f32 v[4:5], v[28:29], v[16:17], v[4:5]
	v_mul_f32_e32 v1, v6, v1
	v_mul_f32_e32 v6, v2, v10
	v_mul_f32_e32 v2, v7, v11
	v_mul_f32_e32 v10, v8, v8
	v_mul_f32_e32 v11, v4, v4
	v_exp_f32_e32 v12, v12
	v_fma_f32 v10, v10, s99, v255
	v_fma_f32 v11, v11, s99, v255
	v_mul_f32_e32 v10, v8, v10
	v_mul_f32_e32 v11, v4, v11
	v_add_f32_e32 v7, 1.0, v12
	v_rcp_f32_e32 v7, v7
	v_exp_f32_e32 v10, v10
	v_exp_f32_e32 v11, v11
	v_mul_f32_e32 v12, v5, v5
	v_mul_f32_e32 v7, v3, v7
	v_add_f32_e32 v3, 1.0, v10
	v_add_f32_e32 v10, 1.0, v11
	v_mul_f32_e32 v11, v9, v9
	v_fma_f32 v11, v11, s99, v255
	v_fma_f32 v12, v12, s99, v255
	v_mul_f32_e32 v11, v9, v11
	v_mul_f32_e32 v12, v5, v12
	v_exp_f32_e32 v11, v11
	v_exp_f32_e32 v12, v12
	v_rcp_f32_e32 v3, v3
	v_rcp_f32_e32 v10, v10
	v_add_f32_e32 v11, 1.0, v11
	v_add_f32_e32 v12, 1.0, v12
	v_rcp_f32_e32 v11, v11
	v_rcp_f32_e32 v12, v12
	v_mul_f32_e32 v3, v8, v3
	v_mul_f32_e32 v8, v4, v10
	v_mul_f32_e32 v4, v9, v11
	v_mul_f32_e32 v5, v5, v12
	v_cvt_pk_bf16_f32 v2, v1, v2
	v_cvt_pk_bf16_f32 v3, v3, v4
	v_cvt_pk_bf16_f32 v4, v6, v7
	v_cvt_pk_bf16_f32 v5, v8, v5
	global_store_dwordx4 v[18:19], v[2:5], off offset:256
	s_waitcnt vmcnt(0)
	s_mov_b32 s53, s80
	s_barrier
